# attention B phase start: first item's Q loads issued before the first-tiles landing wait and barrier (vmcnt 12)
# speedup vs baseline: 1.0034x; 1.0028x over previous
.LBB0_679:
	s_or_b64 exec, exec, s[4:5]
	s_mov_b64 s[10:11], s[40:41]
	s_waitcnt lgkmcnt(0)
	s_barrier
	s_mov_b32 s101, 1
	s_add_u32 s4, s10, 0xd200000
	s_addc_u32 s5, s11, 0
	s_add_u32 s8, s10, 0x13400000
	s_addc_u32 s9, s11, 0
	s_add_u32 s12, s10, 0x1b400000
	s_addc_u32 s13, s11, 0
	v_readlane_b32 s0, v254, 5
	s_add_u32 s0, s12, s0
	v_readlane_b32 s1, v254, 4
	v_mbcnt_lo_u32_b32 v0, -1, 0
	v_mbcnt_hi_u32_b32 v0, -1, v0
	s_addc_u32 s1, s13, s1
	v_add_u32_e32 v6, s69, v0
	v_readlane_b32 s6, v254, 6
	v_readlane_b32 s7, v254, 7
	s_add_u32 s20, s0, s6
	v_bfe_u32 v0, v6, 4, 2
	v_readlane_b32 s0, v252, 52
	s_addc_u32 s21, s1, s7
	v_and_b32_e32 v3, 15, v6
	v_or_b32_e32 v2, s0, v0
	v_lshlrev_b32_e32 v0, 2, v0
	v_readlane_b32 s0, v254, 8
	v_mul_lo_u32 v2, v2, s43
	v_bitop3_b32 v0, v0, v3, s84 bitop3:0x36
	s_add_u32 s0, s20, s0
	v_lshl_or_b32 v118, v0, 4, v2
	v_mov_b32_e32 v119, v1
	s_addc_u32 s1, s21, 0
	v_lshl_add_u64 v[2:3], s[0:1], 0, v[118:119]
	s_mov_b32 s0, 0xfff20000
	s_mov_b32 s1, -1
	v_lshl_add_u64 v[4:5], v[2:3], 0, s[0:1]
	s_mov_b32 s0, 0xfff20600
	s_mov_b32 m0, s85
	s_mov_b32 s1, -1
	global_load_lds_dwordx4 v[4:5], off
	v_lshl_add_u64 v[2:3], v[2:3], 0, s[0:1]
	s_add_i32 m0, s85, 0x2000
	v_readlane_b32 s0, v254, 9
	s_add_u32 s0, s20, s0
	s_addc_u32 s1, s21, 0
	global_load_lds_dwordx4 v[2:3], off
	v_lshl_add_u64 v[2:3], s[0:1], 0, v[118:119]
	s_mov_b32 s0, 0xfff90000
	s_mov_b32 s1, -1
	v_lshl_add_u64 v[4:5], v[2:3], 0, s[0:1]
	s_mov_b32 s0, 0xfff90600
	s_add_i32 m0, s85, 0x4000
	s_mov_b32 s1, -1
	v_readlane_b32 s50, v254, 11
	global_load_lds_dwordx4 v[4:5], off
	v_lshl_add_u64 v[2:3], v[2:3], 0, s[0:1]
	s_add_i32 m0, s85, 0x6000
	s_mul_i32 s0, s50, 0x3800
	s_add_u32 s0, s20, s0
	s_addc_u32 s1, s21, 0
	global_load_lds_dwordx4 v[2:3], off
	v_lshl_add_u64 v[2:3], s[0:1], 0, v[118:119]
	s_add_i32 m0, s85, 0x8000
	v_lshl_add_u64 v[4:5], v[2:3], 0, s[92:93]
	global_load_lds_dwordx4 v118, s[0:1]
	s_add_i32 m0, s85, 0xa000
	s_mov_b64 s[0:1], 0x70000
	global_load_lds_dwordx4 v[4:5], off
	v_lshl_add_u64 v[4:5], v[2:3], 0, s[0:1]
	s_mov_b64 s[0:1], 0x70600
	v_lshl_add_u64 v[2:3], v[2:3], 0, s[0:1]
	v_and_b32_e32 v7, 31, v6
	v_readlane_b32 s0, v254, 12
	s_add_i32 m0, s85, 0xc000
	v_mov_b32_e32 v121, v1
	v_or_b32_e32 v0, s0, v7
	v_readlane_b32 s0, v253, 14
	global_load_lds_dwordx4 v[4:5], off
	s_add_i32 m0, s85, 0xe000
	v_readlane_b32 s1, v253, 15
	global_load_lds_dwordx4 v[2:3], off
	s_nop 0
	v_lshl_add_u64 v[2:3], s[0:1], 0, v[0:1]
	v_mov_b64_e32 v[4:5], s[12:13]
	v_mad_u64_u32 v[4:5], s[0:1], v2, s43, v[4:5]
	v_readlane_b32 s0, v254, 13
	v_mad_i32_i24 v5, v3, s43, v5
	v_readlane_b32 s1, v254, 14
	v_lshrrev_b32_e32 v0, 1, v6
	v_and_b32_e32 v120, 16, v0
	v_lshl_add_u64 v[2:3], v[4:5], 0, s[0:1]
	v_lshl_add_u64 v[2:3], v[2:3], 0, v[120:121]
	global_load_dwordx4 v[82:85], v[2:3], off
	global_load_dwordx4 v[86:89], v[2:3], off offset:32
	global_load_dwordx4 v[90:93], v[2:3], off offset:64
	global_load_dwordx4 v[94:97], v[2:3], off offset:96
	global_load_dwordx4 v[98:101], v[2:3], off offset:128
	global_load_dwordx4 v[102:105], v[2:3], off offset:160
	global_load_dwordx4 v[106:109], v[2:3], off offset:192
	global_load_dwordx4 v[110:113], v[2:3], off offset:224
	s_waitcnt vmcnt(12)
	s_waitcnt lgkmcnt(0)
	s_barrier
	v_readlane_b32 s0, v253, 4
	v_and_b32_e32 v0, 7, v6
	v_lshlrev_b32_e32 v122, 4, v0
	v_mov_b32_e32 v2, s0
	s_movk_i32 s0, 0x90
	v_bfe_u32 v124, v6, 3, 3
	v_mov_b32_e32 v123, v1
	v_mad_u32_u24 v129, v7, s0, v2
	v_mad_u32_u24 v131, v124, s0, v2
	v_lshl_add_u64 v[4:5], s[10:11], 0, v[122:123]
	s_mov_b64 s[0:1], 0xd400000
	v_lshl_add_u64 v[132:133], v[4:5], 0, s[0:1]
	s_mov_b64 s[0:1], 0x10400000
	v_bfe_u32 v3, v6, 5, 1
	v_lshlrev_b32_e32 v0, 3, v0
	v_lshl_add_u64 v[134:135], v[4:5], 0, s[0:1]
	v_readlane_b32 s0, v254, 32
	v_and_b32_e32 v125, 63, v6
	v_lshlrev_b32_e32 v8, 3, v3
	v_or_b32_e32 v2, 64, v0
	v_lshl_add_u32 v3, v3, 2, s0
	s_mov_b32 s19, 4
	v_or_b32_e32 v127, s31, v7
	v_cmp_gt_u32_e64 s[6:7], 32, v125
	v_or_b32_e32 v126, 8, v124
	v_or_b32_e32 v128, 16, v124
	v_or_b32_e32 v130, 24, v124
	v_add_u32_e32 v217, 0x480, v131
	v_add_u32_e32 v218, 0x900, v131
	v_add_u32_e32 v219, 0xd80, v131
	v_sub_u32_e32 v123, v3, v7
	s_mov_b32 s28, 0
	s_mov_b64 s[24:25], 0
	v_lshlrev_b32_e32 v136, 1, v0
	v_lshlrev_b32_e32 v138, 1, v2
	v_add_u32_e32 v220, v129, v8
	s_mov_b32 s51, 4
	s_mov_b32 s49, s66
	s_mov_b32 s48, 0
	s_mov_b32 s29, s66
	v_and_b32_e32 v240, 31, v125
	v_lshrrev_b32_e32 v241, 5, v125
	v_lshlrev_b32_e32 v242, 2, v125
	v_and_b32_e32 v242, 12, v242
	v_bfe_u32 v243, v125, 2, 2
	v_or_b32_e32 v242, v242, v243
	v_xor_b32_e32 v244, v241, v242
	v_lshlrev_b32_e32 v244, 4, v244
	v_lshl_add_u32 v238, v240, 8, v244
	v_lshl_or_b32 v245, v241, 2, v243
	v_lshlrev_b32_e32 v246, 2, v243
	v_or_b32_e32 v246, v246, v241
	v_bfe_u32 v247, v125, 1, 1
	v_lshrrev_b32_e32 v248, 3, v125
	v_and_or_b32 v247, v248, 2, v247
	v_xor_b32_e32 v247, v247, v246
	v_lshlrev_b32_e32 v247, 4, v247
	v_lshl_add_u32 v247, v245, 8, v247
	v_lshlrev_b32_e32 v248, 3, v125
	v_and_b32_e32 v248, 8, v248
	v_add_u32_e32 v239, v247, v248
	v_add_u32_e32 v239, 0x2000, v239
	s_waitcnt vmcnt(0)
	s_branch .LBB0_681
